# MLA smax loop: next key tile written to LDS right after the V fragment reads (before softmax/PV) with load-counted vmcnt; barriers stay at step ends
# speedup vs baseline: 1.0073x; 1.0073x over previous
; template <int DQK, bool NA, bool SMAX, int LDV> ...
;     ...
;     for (int i = 0; i < NKC; ++i) if (kval[i]) *(u32x4*)(smem + kkey[i] * KSTR + kcc[i] * 16) = rkA[i];
;     *(u32x4*)(smem + KBYTES + vdv * VSTR + vcc * 16) = rvA;
;   }
;   __syncthreads();
;   f32x4 o[4][2];
;   float mrun[2], lrun[2];
; #pragma unroll
;   for (int qt = 0; qt < 2; ++qt) {
;     mrun[qt] = -1e30f; lrun[qt] = 0.f;
; #pragma unroll
;     for (int d = 0; d < 4; ++d) o[d][qt] = (f32x4){0.f, 0.f, 0.f, 0.f};
;   }
;     ...
;     if (more) {
;       char* nx = smem + (cur ^ 1) * STG;
; #pragma unroll
;       for (int i = 0; i < NKC; ++i) if (kval[i]) *(u32x4*)(nx + kkey[i] * KSTR + kcc[i] * 16) = rk_wr[i];
;       *(u32x4*)(nx + KBYTES + vdv * VSTR + vcc * 16) = rv_wr;
;     }
;     __syncthreads();
;   };
;   for (int it = 0; it < nkt; it += 2) {
;     step(it, rkA, rvA, rkB, rvB);
;     if (it + 1 < nkt) step(it + 1, rkB, rvB, rkA, rvA);
;   }
.LBB0_1133:
	s_or_b64 exec, exec, s[4:5]
	s_movk_i32 s26, 0x600
	v_mad_i64_i32 v[64:65], s[4:5], v14, s26, 0
	v_mad_i64_i32 v[14:15], s[4:5], v15, s26, 0
	s_movk_i32 s4, 0xa0
	s_nop 0
	v_mul_lo_u32 v6, v6, s4
	v_add_u32_e32 v6, 0, v6
	v_add_u32_e32 v173, v6, v0
	v_lshlrev_b32_e32 v172, 2, v13
	v_lshrrev_b32_e32 v6, 2, v12
	s_add_u32 s4, s53, s52
	v_or_b32_e32 v6, v172, v6
	s_addc_u32 s5, 0, 0
	v_lshl_add_u32 v11, v13, 4, 0
	v_mul_u32_u24_e32 v13, 0xa0, v6
	v_add_u32_e32 v174, 0, v7
	v_lshl_add_u64 v[6:7], s[4:5], 0, v[8:9]
	s_add_u32 s4, s33, s19
	s_addc_u32 s5, 0, 0
	v_mul_u32_u24_e32 v66, 0xe0, v12
	v_lshlrev_b32_e32 v12, 3, v12
	v_lshl_add_u64 v[120:121], v[6:7], 0, v[0:1]
	v_lshl_add_u64 v[6:7], s[4:5], 0, v[14:15]
	v_and_b32_e32 v12, 24, v12
	v_lshl_add_u64 v[124:125], v[4:5], 1, v[6:7]
	v_lshl_add_u64 v[4:5], s[4:5], 0, v[64:65]
	v_add_u32_e32 v12, 0, v12
	v_lshl_add_u64 v[126:127], v[2:3], 1, v[4:5]
	v_mov_b32_e32 v4, 0
	v_ashrrev_i32_e32 v119, 31, v118
	v_ashrrev_i32_e32 v117, 31, v116
	v_add_u32_e32 v175, 0, v10
	s_mov_b32 s19, 0
	v_add_u32_e32 v0, v11, v66
	v_add_u32_e32 v176, v12, v13
	v_mov_b32_e32 v5, v4
	v_mov_b32_e32 v6, v4
	v_mov_b32_e32 v7, v4
	v_mov_b32_e32 v64, v4
	v_mov_b32_e32 v65, v4
	v_mov_b32_e32 v66, v4
	v_mov_b32_e32 v67, v4
	v_mov_b32_e32 v8, v4
	v_mov_b32_e32 v9, v4
	v_mov_b32_e32 v10, v4
	v_mov_b32_e32 v11, v4
	v_mov_b32_e32 v68, v4
	v_mov_b32_e32 v69, v4
	v_mov_b32_e32 v70, v4
	v_mov_b32_e32 v71, v4
	v_mov_b32_e32 v12, v4
	v_mov_b32_e32 v13, v4
	v_mov_b32_e32 v14, v4
	v_mov_b32_e32 v15, v4
	v_mov_b32_e32 v76, v4
	v_mov_b32_e32 v77, v4
	v_mov_b32_e32 v78, v4
	v_mov_b32_e32 v79, v4
	v_mov_b32_e32 v72, v4
	v_mov_b32_e32 v73, v4
	v_mov_b32_e32 v74, v4
	v_mov_b32_e32 v75, v4
	v_mov_b32_e32 v80, v4
	v_mov_b32_e32 v81, v4
	v_mov_b32_e32 v82, v4
	v_mov_b32_e32 v83, v4
	v_mov_b32_e32 v122, v4
	v_mov_b32_e32 v123, v4
	s_waitcnt vmcnt(3)
	ds_write_b128 v173, v[52:55] offset:14336
	s_waitcnt lgkmcnt(0)
	s_barrier
	v_sub_f32_e32 v244, 0, v188
	v_sub_f32_e32 v245, 0, v188
	v_sub_f32_e32 v246, 0, v188
	v_sub_f32_e32 v247, 0, v188
	s_branch .LBB0_1136
.LBB0_1135:
	s_nop 1
	v_add_f32_e32 v2, 0, v177
	v_add_f32_e32 v2, v178, v2
	v_add_f32_e32 v2, v179, v2
	v_add_f32_e32 v84, 0, v205
	v_add_f32_e32 v2, v180, v2
	v_add_f32_e32 v84, v206, v84
	v_add_f32_e32 v2, v181, v2
	v_add_f32_e32 v84, v207, v84
	v_add_f32_e32 v2, v182, v2
	v_add_f32_e32 v84, v208, v84
	v_add_f32_e32 v3, v183, v2
	v_add_f32_e32 v2, 0, v184
	v_add_f32_e32 v84, v209, v84
	v_add_f32_e32 v2, v185, v2
	v_add_f32_e32 v85, v210, v84
	v_add_f32_e32 v84, 0, v211
	v_add_f32_e32 v2, v186, v2
	v_add_f32_e32 v84, v212, v84
	v_add_f32_e32 v2, v187, v2
	v_add_f32_e32 v84, v213, v84
	v_add_f32_e32 v2, v189, v2
	v_add_f32_e32 v84, v214, v84
	v_add_f32_e32 v2, v203, v2
	v_add_f32_e32 v84, v215, v84
	v_add_f32_e32 v2, v204, v2
	v_add_f32_e32 v84, v216, v84
	v_pk_add_f32 v[2:3], v[128:129], v[2:3]
	v_pk_add_f32 v[84:85], v[146:147], v[84:85]
	v_pk_add_f32 v[2:3], v[130:131], v[2:3]
	v_pk_add_f32 v[84:85], v[154:155], v[84:85]
	v_pk_add_f32 v[2:3], v[132:133], v[2:3]
	v_pk_add_f32 v[84:85], v[156:157], v[84:85]
	v_pk_add_f32 v[2:3], v[134:135], v[2:3]
	v_pk_add_f32 v[84:85], v[158:159], v[84:85]
	v_pk_add_f32 v[2:3], v[136:137], v[2:3]
	v_pk_add_f32 v[84:85], v[160:161], v[84:85]
	v_pk_add_f32 v[2:3], v[138:139], v[2:3]
	v_pk_add_f32 v[84:85], v[162:163], v[84:85]
	v_pk_add_f32 v[2:3], v[140:141], v[2:3]
	v_pk_add_f32 v[84:85], v[164:165], v[84:85]
	v_pk_add_f32 v[2:3], v[142:143], v[2:3]
	v_pk_add_f32 v[84:85], v[166:167], v[84:85]
	v_pk_add_f32 v[2:3], v[144:145], v[2:3]
	v_pk_add_f32 v[84:85], v[168:169], v[84:85]
	v_pk_add_f32 v[2:3], v[122:123], v[2:3]
	v_pk_add_f32 v[84:85], v[170:171], v[84:85]
	s_add_i32 s19, s19, 2
	v_pk_add_f32 v[122:123], v[2:3], v[84:85]
	v_lshl_add_u64 v[120:121], v[120:121], 0, s[24:25]
	v_lshl_add_u64 v[124:125], v[124:125], 0, s[16:17]
	s_andn2_b64 vcc, exec, s[4:5]
	v_lshl_add_u64 v[126:127], v[126:127], 0, s[16:17]
	s_waitcnt lgkmcnt(0)
	s_barrier
	s_cbranch_vccz .LBB0_992

; template <int DQK, bool NA, bool SMAX, int LDV> ...
;     ...
;     const char* ks = smem + cur * STG;
;     const char* vs = ks + KBYTES;
;     f32x4 s[4][2];
; #pragma unroll
;     for (int kt = 0; kt < 4; ++kt) { s[kt][0] = (f32x4){0.f, 0.f, 0.f, 0.f}; s[kt][1] = (f32x4){0.f, 0.f, 0.f, 0.f}; }
; #pragma unroll
;     for (int ds = 0; ds < NDS; ++ds) {
;       bf16x8 kf[4];
; #pragma unroll
;       for (int kt = 0; kt < 4; ++kt) kf[kt] = *(const bf16x8*)(ks + (kt * 16 + fr) * KSTR + ds * 64 + fq * 16);
; #pragma unroll
;       for (int kt = 0; kt < 4; ++kt) {
;         s[kt][0] = __builtin_amdgcn_mfma_f32_16x16x32_bf16(kf[kt], qf[0][ds], s[kt][0], 0, 0, 0);
;         s[kt][1] = __builtin_amdgcn_mfma_f32_16x16x32_bf16(kf[kt], qf[1][ds], s[kt][1], 0, 0, 0);
;       }
;     }
;     bf16x8 vfr[2][4];
; #pragma unroll
;     for (int k2 = 0; k2 < 2; ++k2)
; #pragma unroll
;       for (int d = 0; d < 4; ++d) {
;         const char* vp = vs + (k2 * 32 + fq * 4 + (fr >> 2)) * VSTR + d * 32 + (fr & 3) * 8;
;         typedef short s16x4_t __attribute__((ext_vector_type(4)));
;         const s16x4_t lo = __builtin_amdgcn_ds_read_tr16_b64_v4i16((__attribute__((address_space(3))) s16x4_t*)(vp));
;         const s16x4_t hi = __builtin_amdgcn_ds_read_tr16_b64_v4i16((__attribute__((address_space(3))) s16x4_t*)(vp + 16 * VSTR));
;         vfr[k2][d] = __builtin_shufflevector(lo, hi, 0, 1, 2, 3, 4, 5, 6, 7);
;       }
;     ...
; #pragma unroll
;     for (int k2 = 0; k2 < 2; ++k2) {
;       bf16x8 pf[2];
; #pragma unroll
;       for (int qt = 0; qt < 2; ++qt) {
;         u32x4 u;
;         u[0] = cvt_pk_bf16(s[2 * k2][qt][0], s[2 * k2][qt][1]); u[1] = cvt_pk_bf16(s[2 * k2][qt][2], s[2 * k2][qt][3]);
;         u[2] = cvt_pk_bf16(s[2 * k2 + 1][qt][0], s[2 * k2 + 1][qt][1]); u[3] = cvt_pk_bf16(s[2 * k2 + 1][qt][2], s[2 * k2 + 1][qt][3]);
;         pf[qt] = __builtin_bit_cast(bf16x8, u);
;       }
; #pragma unroll
;       for (int d = 0; d < 4; ++d) {
;         o[d][0] = __builtin_amdgcn_mfma_f32_16x16x32_bf16(vfr[k2][d], pf[0], o[d][0], 0, 0, 0);
;         o[d][1] = __builtin_amdgcn_mfma_f32_16x16x32_bf16(vfr[k2][d], pf[1], o[d][1], 0, 0, 0);
;       }
;     }
;     if (more) {
;       char* nx = smem + (cur ^ 1) * STG;
; #pragma unroll
;       for (int i = 0; i < NKC; ++i) if (kval[i]) *(u32x4*)(nx + kkey[i] * KSTR + kcc[i] * 16) = rk_wr[i];
.LBB0_1138:
	ds_read_b128 v[84:87], v0
	ds_read_b128 v[88:91], v0 offset:3584
	ds_read_b128 v[92:95], v0 offset:7168
	ds_read_b128 v[96:99], v0 offset:10752
	ds_read_b128 v[128:131], v0 offset:64
	ds_read_b128 v[132:135], v0 offset:3648
	ds_read_b128 v[136:139], v0 offset:7232
	ds_read_b128 v[140:143], v0 offset:10816
	s_waitcnt lgkmcnt(7)
	v_mfma_f32_16x16x32_bf16 v[100:103], v[84:87], v[16:19], v[244:247]
	v_mfma_f32_16x16x32_bf16 v[84:87], v[84:87], v[28:31], v[244:247]
	s_waitcnt lgkmcnt(6)
	v_mfma_f32_16x16x32_bf16 v[104:107], v[88:91], v[16:19], v[244:247]
	v_mfma_f32_16x16x32_bf16 v[88:91], v[88:91], v[28:31], v[244:247]
	s_waitcnt lgkmcnt(5)
	v_mfma_f32_16x16x32_bf16 v[108:111], v[92:95], v[16:19], v[244:247]
	v_mfma_f32_16x16x32_bf16 v[92:95], v[92:95], v[28:31], v[244:247]
	s_waitcnt lgkmcnt(4)
	v_mfma_f32_16x16x32_bf16 v[112:115], v[96:99], v[16:19], v[244:247]
	v_mfma_f32_16x16x32_bf16 v[96:99], v[96:99], v[28:31], v[244:247]
	s_waitcnt lgkmcnt(3)
	v_mfma_f32_16x16x32_bf16 v[100:103], v[128:131], v[20:23], v[100:103]
	v_mfma_f32_16x16x32_bf16 v[84:87], v[128:131], v[32:35], v[84:87]
	s_waitcnt lgkmcnt(2)
	v_mfma_f32_16x16x32_bf16 v[104:107], v[132:135], v[20:23], v[104:107]
	v_mfma_f32_16x16x32_bf16 v[88:91], v[132:135], v[32:35], v[88:91]
	s_waitcnt lgkmcnt(1)
	v_mfma_f32_16x16x32_bf16 v[108:111], v[136:139], v[20:23], v[108:111]
	v_mfma_f32_16x16x32_bf16 v[92:95], v[136:139], v[32:35], v[92:95]
	s_waitcnt lgkmcnt(0)
	v_mfma_f32_16x16x32_bf16 v[112:115], v[140:143], v[20:23], v[112:115]
	v_mfma_f32_16x16x32_bf16 v[96:99], v[140:143], v[32:35], v[96:99]
	ds_read_b128 v[128:131], v0 offset:128
	ds_read_b128 v[132:135], v0 offset:3712
	ds_read_b128 v[136:139], v0 offset:7296
	ds_read_b128 v[140:143], v0 offset:10880
	s_waitcnt lgkmcnt(3)
	v_mfma_f32_16x16x32_bf16 v[158:161], v[128:131], v[24:27], v[100:103]
	v_mfma_f32_16x16x32_bf16 v[162:165], v[128:131], v[36:39], v[84:87]
	s_waitcnt lgkmcnt(2)
	v_mfma_f32_16x16x32_bf16 v[128:131], v[132:135], v[24:27], v[104:107]
	v_mfma_f32_16x16x32_bf16 v[166:169], v[132:135], v[36:39], v[88:91]
	s_waitcnt lgkmcnt(1)
	v_mfma_f32_16x16x32_bf16 v[184:187], v[136:139], v[24:27], v[108:111]
	v_mfma_f32_16x16x32_bf16 v[206:209], v[136:139], v[36:39], v[92:95]
	s_waitcnt lgkmcnt(0)
	v_mfma_f32_16x16x32_bf16 v[210:213], v[140:143], v[24:27], v[112:115]
	v_mfma_f32_16x16x32_bf16 v[214:217], v[140:143], v[36:39], v[96:99]
	s_nop 1
	ds_read_b64_tr_b16 v[114:115], v176 offset:16896
	ds_read_b64_tr_b16 v[112:113], v176 offset:14336
	ds_read_b64_tr_b16 v[108:109], v176 offset:14368
	ds_read_b64_tr_b16 v[110:111], v176 offset:16928
	ds_read_b64_tr_b16 v[104:105], v176 offset:14400
	ds_read_b64_tr_b16 v[106:107], v176 offset:16960
	ds_read_b64_tr_b16 v[96:97], v176 offset:14432
	ds_read_b64_tr_b16 v[98:99], v176 offset:16992
	ds_read_b64_tr_b16 v[84:85], v176 offset:19456
	ds_read_b64_tr_b16 v[86:87], v176 offset:22016
	ds_read_b64_tr_b16 v[88:89], v176 offset:19488
	ds_read_b64_tr_b16 v[90:91], v176 offset:22048
	ds_read_b64_tr_b16 v[92:93], v176 offset:19520
	ds_read_b64_tr_b16 v[94:95], v176 offset:22080
	ds_read_b64_tr_b16 v[100:101], v176 offset:19552
	ds_read_b64_tr_b16 v[102:103], v176 offset:22112
	s_and_b64 vcc, exec, s[4:5]
	s_cbranch_vccz .Lmla_x_cnt
	s_waitcnt vmcnt(0)
.Lmla_x_cnt:
	s_and_saveexec_b64 s[42:43], s[40:41]
	s_cbranch_execz .LBB0_1140
	v_add_u32_e32 v132, v174, v150
	s_waitcnt vmcnt(5)
	ds_write_b128 v132, v[48:51] offset:24576
.LBB0_1140:
	s_or_b64 exec, exec, s[42:43]
	s_and_saveexec_b64 s[42:43], s[48:49]
	s_cbranch_execz .LBB0_1142
	v_add_u32_e32 v132, v175, v152
	s_waitcnt vmcnt(4)
	ds_write_b128 v132, v[56:59] offset:24576
.LBB0_1142:
	s_or_b64 exec, exec, s[42:43]
	s_cmp_gt_u32 s19, 32
	s_waitcnt vmcnt(3)
	ds_write_b128 v173, v[60:63] offset:38912
	v_exp_f32_e32 v177, v158
	v_exp_f32_e32 v178, v159
	v_exp_f32_e32 v179, v160
	v_exp_f32_e32 v180, v161
	v_exp_f32_e32 v181, v128
	v_exp_f32_e32 v182, v129
	v_exp_f32_e32 v183, v130
	v_exp_f32_e32 v129, v131
	v_exp_f32_e32 v131, v184
	v_exp_f32_e32 v133, v185
	v_exp_f32_e32 v135, v186
	v_exp_f32_e32 v137, v187
	v_exp_f32_e32 v139, v210
	v_exp_f32_e32 v141, v211
	v_exp_f32_e32 v143, v212
	v_exp_f32_e32 v145, v213
	v_exp_f32_e32 v184, v162
	v_exp_f32_e32 v185, v163
	v_exp_f32_e32 v186, v164
	v_exp_f32_e32 v187, v165
	v_exp_f32_e32 v189, v166
	v_exp_f32_e32 v203, v167
	v_exp_f32_e32 v204, v168
	v_exp_f32_e32 v128, v169
	v_exp_f32_e32 v130, v206
	v_exp_f32_e32 v132, v207
	v_exp_f32_e32 v134, v208
	v_exp_f32_e32 v136, v209
	v_exp_f32_e32 v138, v214
	v_exp_f32_e32 v140, v215
	v_exp_f32_e32 v142, v216
	v_exp_f32_e32 v144, v217
	v_cvt_pk_bf16_f32 v158, v177, v178
	v_cvt_pk_bf16_f32 v159, v179, v180
	v_cvt_pk_bf16_f32 v160, v181, v182
	v_cvt_pk_bf16_f32 v161, v183, v129
	v_cvt_pk_bf16_f32 v162, v184, v185
	v_cvt_pk_bf16_f32 v163, v186, v187
	v_cvt_pk_bf16_f32 v164, v189, v203
	v_cvt_pk_bf16_f32 v165, v204, v128
	s_waitcnt lgkmcnt(14)
	v_mfma_f32_16x16x32_bf16 v[80:83], v[112:115], v[158:161], v[80:83]
	v_mfma_f32_16x16x32_bf16 v[72:75], v[112:115], v[162:165], v[72:75]
	s_waitcnt lgkmcnt(12)
	v_mfma_f32_16x16x32_bf16 v[112:115], v[108:111], v[158:161], v[76:79]
	v_mfma_f32_16x16x32_bf16 v[12:15], v[108:111], v[162:165], v[12:15]
	s_waitcnt lgkmcnt(10)
	v_mfma_f32_16x16x32_bf16 v[108:111], v[104:107], v[158:161], v[68:71]
	v_mfma_f32_16x16x32_bf16 v[8:11], v[104:107], v[162:165], v[8:11]
	s_waitcnt lgkmcnt(8)
	v_mfma_f32_16x16x32_bf16 v[104:107], v[96:99], v[158:161], v[64:67]
	v_cvt_pk_bf16_f32 v158, v130, v132
	v_cvt_pk_bf16_f32 v159, v134, v136
	v_cvt_pk_bf16_f32 v160, v138, v140
	v_mfma_f32_16x16x32_bf16 v[2:5], v[96:99], v[162:165], v[4:7]
	v_cvt_pk_bf16_f32 v96, v131, v133
	v_cvt_pk_bf16_f32 v97, v135, v137
	v_cvt_pk_bf16_f32 v98, v139, v141
	v_cvt_pk_bf16_f32 v99, v143, v145
	v_cvt_pk_bf16_f32 v161, v142, v144
	s_waitcnt lgkmcnt(6)
	v_mfma_f32_16x16x32_bf16 v[76:79], v[84:87], v[96:99], v[80:83]
	v_mfma_f32_16x16x32_bf16 v[80:83], v[84:87], v[158:161], v[72:75]
	s_waitcnt lgkmcnt(4)
	v_mfma_f32_16x16x32_bf16 v[72:75], v[88:91], v[96:99], v[112:115]
	v_mfma_f32_16x16x32_bf16 v[68:71], v[88:91], v[158:161], v[12:15]
	s_waitcnt lgkmcnt(2)
	v_mfma_f32_16x16x32_bf16 v[64:67], v[92:95], v[96:99], v[108:111]
	v_mfma_f32_16x16x32_bf16 v[10:13], v[92:95], v[158:161], v[8:11]
	s_waitcnt lgkmcnt(0)
	v_mfma_f32_16x16x32_bf16 v[6:9], v[100:103], v[96:99], v[104:107]
	v_mfma_f32_16x16x32_bf16 v[2:5], v[100:103], v[158:161], v[2:5]
	s_waitcnt lgkmcnt(0)
	s_barrier
	s_cmp_gt_u32 s19, 32
	s_cbranch_scc1 .LBB0_1144
	v_add_co_u32_e32 v14, vcc, 0x10965000, v156
	s_nop 1
	v_addc_co_u32_e32 v15, vcc, 0, v157, vcc
	v_add_co_u32_e32 v56, vcc, 0x10965000, v154
	s_nop 1
	v_addc_co_u32_e32 v57, vcc, 0, v155, vcc
	global_load_dwordx4 v[48:51], v[14:15], off
	s_nop 0
	global_load_dwordx4 v[56:59], v[56:57], off
	v_add_co_u32_e32 v14, vcc, 0x1244d000, v146
	s_nop 1
	v_addc_co_u32_e32 v15, vcc, 0, v147, vcc
	global_load_dwordx4 v[60:63], v[14:15], off
; template <int DQK, bool NA, bool SMAX, int LDV> ...
;     ...
;     const char* ks = smem + cur * STG;
;     const char* vs = ks + KBYTES;
;     f32x4 s[4][2];
; #pragma unroll
;     for (int kt = 0; kt < 4; ++kt) { s[kt][0] = (f32x4){0.f, 0.f, 0.f, 0.f}; s[kt][1] = (f32x4){0.f, 0.f, 0.f, 0.f}; }
; #pragma unroll
;     for (int ds = 0; ds < NDS; ++ds) {
;       bf16x8 kf[4];
; #pragma unroll
;       for (int kt = 0; kt < 4; ++kt) kf[kt] = *(const bf16x8*)(ks + (kt * 16 + fr) * KSTR + ds * 64 + fq * 16);
; #pragma unroll
;       for (int kt = 0; kt < 4; ++kt) {
;         s[kt][0] = __builtin_amdgcn_mfma_f32_16x16x32_bf16(kf[kt], qf[0][ds], s[kt][0], 0, 0, 0);
;         s[kt][1] = __builtin_amdgcn_mfma_f32_16x16x32_bf16(kf[kt], qf[1][ds], s[kt][1], 0, 0, 0);
;       }
;     }
;     bf16x8 vfr[2][4];
; #pragma unroll
;     for (int k2 = 0; k2 < 2; ++k2)
; #pragma unroll
;       for (int d = 0; d < 4; ++d) {
;         const char* vp = vs + (k2 * 32 + fq * 4 + (fr >> 2)) * VSTR + d * 32 + (fr & 3) * 8;
;         typedef short s16x4_t __attribute__((ext_vector_type(4)));
;         const s16x4_t lo = __builtin_amdgcn_ds_read_tr16_b64_v4i16((__attribute__((address_space(3))) s16x4_t*)(vp));
;         const s16x4_t hi = __builtin_amdgcn_ds_read_tr16_b64_v4i16((__attribute__((address_space(3))) s16x4_t*)(vp + 16 * VSTR));
;         vfr[k2][d] = __builtin_shufflevector(lo, hi, 0, 1, 2, 3, 4, 5, 6, 7);
;       }
;     ...
; #pragma unroll
;     for (int k2 = 0; k2 < 2; ++k2) {
;       bf16x8 pf[2];
; #pragma unroll
;       for (int qt = 0; qt < 2; ++qt) {
;         u32x4 u;
;         u[0] = cvt_pk_bf16(s[2 * k2][qt][0], s[2 * k2][qt][1]); u[1] = cvt_pk_bf16(s[2 * k2][qt][2], s[2 * k2][qt][3]);
;         u[2] = cvt_pk_bf16(s[2 * k2 + 1][qt][0], s[2 * k2 + 1][qt][1]); u[3] = cvt_pk_bf16(s[2 * k2 + 1][qt][2], s[2 * k2 + 1][qt][3]);
;         pf[qt] = __builtin_bit_cast(bf16x8, u);
;       }
; #pragma unroll
;       for (int d = 0; d < 4; ++d) {
;         o[d][0] = __builtin_amdgcn_mfma_f32_16x16x32_bf16(vfr[k2][d], pf[0], o[d][0], 0, 0, 0);
;         o[d][1] = __builtin_amdgcn_mfma_f32_16x16x32_bf16(vfr[k2][d], pf[1], o[d][1], 0, 0, 0);
;       }
;     }
;     if (more) {
;       char* nx = smem + (cur ^ 1) * STG;
; #pragma unroll
;       for (int i = 0; i < NKC; ++i) if (kval[i]) *(u32x4*)(nx + kkey[i] * KSTR + kcc[i] * 16) = rk_wr[i];
.LBB0_1144:
	ds_read_b128 v[84:87], v0 offset:24576
	ds_read_b128 v[88:91], v0 offset:28160
	ds_read_b128 v[92:95], v0 offset:31744
	ds_read_b128 v[96:99], v0 offset:35328
	ds_read_b128 v[154:157], v0 offset:24640
	ds_read_b128 v[158:161], v0 offset:28224
	ds_read_b128 v[162:165], v0 offset:31808
	ds_read_b128 v[166:169], v0 offset:35392
	s_waitcnt lgkmcnt(7)
	v_mfma_f32_16x16x32_bf16 v[100:103], v[84:87], v[16:19], v[244:247]
	v_mfma_f32_16x16x32_bf16 v[84:87], v[84:87], v[28:31], v[244:247]
	s_waitcnt lgkmcnt(6)
	v_mfma_f32_16x16x32_bf16 v[104:107], v[88:91], v[16:19], v[244:247]
	v_mfma_f32_16x16x32_bf16 v[88:91], v[88:91], v[28:31], v[244:247]
	s_waitcnt lgkmcnt(5)
	v_mfma_f32_16x16x32_bf16 v[108:111], v[92:95], v[16:19], v[244:247]
	v_mfma_f32_16x16x32_bf16 v[92:95], v[92:95], v[28:31], v[244:247]
	s_waitcnt lgkmcnt(4)
	v_mfma_f32_16x16x32_bf16 v[112:115], v[96:99], v[16:19], v[244:247]
	v_mfma_f32_16x16x32_bf16 v[96:99], v[96:99], v[28:31], v[244:247]
	s_waitcnt lgkmcnt(3)
	v_mfma_f32_16x16x32_bf16 v[100:103], v[154:157], v[20:23], v[100:103]
	v_mfma_f32_16x16x32_bf16 v[84:87], v[154:157], v[32:35], v[84:87]
	s_waitcnt lgkmcnt(2)
	v_mfma_f32_16x16x32_bf16 v[104:107], v[158:161], v[20:23], v[104:107]
	v_mfma_f32_16x16x32_bf16 v[88:91], v[158:161], v[32:35], v[88:91]
	s_waitcnt lgkmcnt(1)
	v_mfma_f32_16x16x32_bf16 v[108:111], v[162:165], v[20:23], v[108:111]
	v_mfma_f32_16x16x32_bf16 v[92:95], v[162:165], v[32:35], v[92:95]
	s_waitcnt lgkmcnt(0)
	v_mfma_f32_16x16x32_bf16 v[112:115], v[166:169], v[20:23], v[112:115]
	v_mfma_f32_16x16x32_bf16 v[96:99], v[166:169], v[32:35], v[96:99]
	ds_read_b128 v[154:157], v0 offset:24704
	ds_read_b128 v[158:161], v0 offset:28288
	ds_read_b128 v[162:165], v0 offset:31872
	ds_read_b128 v[166:169], v0 offset:35456
	s_waitcnt lgkmcnt(3)
	v_mfma_f32_16x16x32_bf16 v[206:209], v[154:157], v[24:27], v[100:103]
	v_mfma_f32_16x16x32_bf16 v[212:215], v[154:157], v[36:39], v[84:87]
	s_waitcnt lgkmcnt(2)
	v_mfma_f32_16x16x32_bf16 v[154:157], v[158:161], v[24:27], v[104:107]
	v_mfma_f32_16x16x32_bf16 v[216:219], v[158:161], v[36:39], v[88:91]
	s_waitcnt lgkmcnt(1)
	v_mfma_f32_16x16x32_bf16 v[220:223], v[162:165], v[24:27], v[108:111]
	v_mfma_f32_16x16x32_bf16 v[224:227], v[162:165], v[36:39], v[92:95]
	s_waitcnt lgkmcnt(0)
	v_mfma_f32_16x16x32_bf16 v[228:231], v[166:169], v[24:27], v[112:115]
	v_mfma_f32_16x16x32_bf16 v[232:235], v[166:169], v[36:39], v[96:99]
	s_nop 1
	ds_read_b64_tr_b16 v[114:115], v176 offset:41472
	ds_read_b64_tr_b16 v[112:113], v176 offset:38912
	ds_read_b64_tr_b16 v[108:109], v176 offset:38944
	ds_read_b64_tr_b16 v[110:111], v176 offset:41504
	ds_read_b64_tr_b16 v[104:105], v176 offset:38976
	ds_read_b64_tr_b16 v[106:107], v176 offset:41536
	ds_read_b64_tr_b16 v[96:97], v176 offset:39008
	ds_read_b64_tr_b16 v[98:99], v176 offset:41568
	ds_read_b64_tr_b16 v[84:85], v176 offset:44032
	ds_read_b64_tr_b16 v[86:87], v176 offset:46592
	ds_read_b64_tr_b16 v[88:89], v176 offset:44064
	ds_read_b64_tr_b16 v[90:91], v176 offset:46624
	ds_read_b64_tr_b16 v[92:93], v176 offset:44096
	ds_read_b64_tr_b16 v[94:95], v176 offset:46656
	ds_read_b64_tr_b16 v[100:101], v176 offset:44128
	ds_read_b64_tr_b16 v[102:103], v176 offset:46688
	s_andn2_b64 vcc, exec, s[26:27]
	s_cbranch_vccnz .Lmla_x_noW2
	s_and_saveexec_b64 s[26:27], s[40:41]
	s_nop 0
	v_add_u32_e32 v160, v174, v150
	s_waitcnt vmcnt(5)
	ds_write_b128 v160, v[40:43]
	s_or_b64 exec, exec, s[26:27]
	s_and_saveexec_b64 s[26:27], s[48:49]
	s_cbranch_execz .Lmla_x_1134
	v_add_u32_e32 v160, v175, v152
	s_waitcnt vmcnt(4)
	ds_write_b128 v160, v[44:47]
.Lmla_x_1134:
	s_or_b64 exec, exec, s[26:27]
	s_waitcnt vmcnt(3)
	ds_write_b128 v173, v[52:55] offset:14336
.Lmla_x_noW2:
	v_exp_f32_e32 v205, v206
	v_exp_f32_e32 v206, v207
	v_exp_f32_e32 v207, v208
	v_exp_f32_e32 v208, v209
	v_exp_f32_e32 v209, v154
	v_exp_f32_e32 v210, v155
	v_exp_f32_e32 v147, v156
	v_exp_f32_e32 v155, v157
	v_exp_f32_e32 v157, v220
	v_exp_f32_e32 v159, v221
	v_exp_f32_e32 v161, v222
	v_exp_f32_e32 v163, v223
	v_exp_f32_e32 v165, v228
	v_exp_f32_e32 v167, v229
	v_exp_f32_e32 v169, v230
	v_exp_f32_e32 v171, v231
	v_exp_f32_e32 v211, v212
	v_exp_f32_e32 v212, v213
	v_exp_f32_e32 v213, v214
	v_exp_f32_e32 v214, v215
	v_exp_f32_e32 v215, v216
	v_exp_f32_e32 v216, v217
	v_exp_f32_e32 v146, v218
	v_exp_f32_e32 v154, v219
	v_exp_f32_e32 v156, v224
	v_exp_f32_e32 v158, v225
	v_exp_f32_e32 v160, v226
	v_exp_f32_e32 v162, v227
	v_exp_f32_e32 v164, v232
	v_exp_f32_e32 v166, v233
	v_exp_f32_e32 v168, v234
	v_exp_f32_e32 v170, v235
	v_cvt_pk_bf16_f32 v218, v205, v206
	v_cvt_pk_bf16_f32 v219, v207, v208
	v_cvt_pk_bf16_f32 v220, v209, v210
	v_cvt_pk_bf16_f32 v221, v147, v155
	v_cvt_pk_bf16_f32 v222, v211, v212
	v_cvt_pk_bf16_f32 v223, v213, v214
	v_cvt_pk_bf16_f32 v224, v215, v216
	v_cvt_pk_bf16_f32 v225, v146, v154
	s_waitcnt lgkmcnt(14)
	v_mfma_f32_16x16x32_bf16 v[76:79], v[112:115], v[218:221], v[76:79]
	v_mfma_f32_16x16x32_bf16 v[112:115], v[112:115], v[222:225], v[80:83]
	s_waitcnt lgkmcnt(12)
	v_mfma_f32_16x16x32_bf16 v[226:229], v[108:111], v[218:221], v[72:75]
	v_mfma_f32_16x16x32_bf16 v[68:71], v[108:111], v[222:225], v[68:71]
	s_waitcnt lgkmcnt(10)
	v_mfma_f32_16x16x32_bf16 v[64:67], v[104:107], v[218:221], v[64:67]
	v_mfma_f32_16x16x32_bf16 v[104:107], v[104:107], v[222:225], v[10:13]
	s_waitcnt lgkmcnt(8)
	v_mfma_f32_16x16x32_bf16 v[108:111], v[96:99], v[218:221], v[6:9]
	v_cvt_pk_bf16_f32 v218, v156, v158
	v_cvt_pk_bf16_f32 v219, v160, v162
	v_cvt_pk_bf16_f32 v220, v164, v166
	v_mfma_f32_16x16x32_bf16 v[2:5], v[96:99], v[222:225], v[2:5]
	v_cvt_pk_bf16_f32 v96, v157, v159
	v_cvt_pk_bf16_f32 v97, v161, v163
	v_cvt_pk_bf16_f32 v98, v165, v167
	v_cvt_pk_bf16_f32 v99, v169, v171
	v_cvt_pk_bf16_f32 v221, v168, v170
	s_waitcnt lgkmcnt(6)
	v_mfma_f32_16x16x32_bf16 v[80:83], v[84:87], v[96:99], v[76:79]
	v_mfma_f32_16x16x32_bf16 v[72:75], v[84:87], v[218:221], v[112:115]
	s_waitcnt lgkmcnt(4)
	v_mfma_f32_16x16x32_bf16 v[76:79], v[88:91], v[96:99], v[226:229]
	v_mfma_f32_16x16x32_bf16 v[12:15], v[88:91], v[218:221], v[68:71]
	s_waitcnt lgkmcnt(2)
	v_mfma_f32_16x16x32_bf16 v[68:71], v[92:95], v[96:99], v[64:67]
	v_mfma_f32_16x16x32_bf16 v[8:11], v[92:95], v[218:221], v[104:107]
	s_waitcnt lgkmcnt(0)
	v_mfma_f32_16x16x32_bf16 v[64:67], v[100:103], v[96:99], v[108:111]
	v_mfma_f32_16x16x32_bf16 v[4:7], v[100:103], v[218:221], v[2:5]
	s_branch .LBB0_1135
